# v98 plus attention phase start stagger: odd XCDs (same K/V as their even neighbour) 1.4 us late
# baseline (speedup 1.0000x reference)
; DI int v_st(int k, int c) { const int kk = (k & ~0xC) | ((k & 4) << 1) | ((k & 8) >> 1); return ((kk >> 3) * 4 + (c >> 5)) * 512 + ((kk & 7) * 32 + (c & 31)) * 2; }
; DI int v_rd_base(int lane) { return ((lane & 3) << 3) | (((lane >> 2) & 3) << 6) | (((lane >> 4) & 1) << 5) | (((lane >> 5) & 1) << 8); }
; DI void attn_item(const bf16_t* __restrict__ Qw_, const bf16_t* __restrict__ Kh, const bf16_t* __restrict__ Vh, const bf16_t* Gw, bf16_t* Ow,
;                   int NT, int kt0, int qw, float sinkv, char* lds) {
;     const int tid = threadIdx.x, wid = __builtin_amdgcn_readfirstlane(tid >> 6), lane = tid & 63, r32 = lane & 31, hi = lane >> 5;
;     char* V_lds = lds; char* K_lds = lds + 2 * SHM_V;
;     float* wsp = (float*)(lds + 2 * SHM_V + 2 * SHM_K) + wid * 64; float* li_l = wsp; float* al_l = wsp + 32;
;     float m_reg = sinkv * (1.f / SCALE), l_reg = 1.f; f32x16 o[4]; bf16x8 qr[8];
; #pragma unroll
;     for (int d = 0; d < 4; ++d)
; #pragma unroll
;         for (int r = 0; r < 16; ++r) o[d][r] = 0.f;
;     const bf16_t* Qw = Qw_ + (size_t)r32 * LDK + hi * 8;
; #pragma unroll
;     for (int d0 = 0; d0 < 8; ++d0) qr[d0] = *(const bf16x8*)(Qw + d0 * 16);
;     const int sr = tid >> 4, sc = (tid & 15) * 8, vst0 = v_st(sr, sc), vst1 = v_st(32 + sr, sc);
;     const int vb0 = (int)(uintptr_t)V_lds + v_rd_base(lane);
; DI void phase_att(const Params& p, unsigned char* shm) {
;     const int wid = __builtin_amdgcn_readfirstlane(threadIdx.x >> 6);
;     const bf16_t* Z = (const bf16_t*)(p.ws + WS_ZQKV); const bf16_t* GA = (const bf16_t*)(p.ws + WS_ZGA); bf16_t* YB = (bf16_t*)(p.ws + WS_YB);
;     for (int it = blockIdx.x; it < 1024; it += gridDim.x) {
;         const int hp = it & 1, g = (it >> 1) & 3, n = it >> 3;
;         const int head = g * 4 + hp * 2 + (wid >> 2), qw = 32 * (wid & 3);
;         const int kfirst = n == 0 ? 0 : (n - 1) * 128, NT = (n == 0 || n == 127) ? 4 : 6, kt0 = kfirst - n * 128;
.LBB0_234:
	s_bitcmp0_b32 s4, 1
	s_cbranch_scc1 .LBB0_266
	s_bitcmp1_b32 s2, 0
	s_cbranch_scc0 .Latt_nostagx
	s_sleep 38
.Latt_nostagx:
	s_cmpk_gt_i32 s2, 0x3ff
	v_readfirstlane_b32 s6, v202
	s_cbranch_scc1 .LBB0_265
	v_lshrrev_b32_e32 v180, 4, v202
	s_load_dwordx2 s[4:5], s[0:1], 0x80
	s_load_dwordx2 s[8:9], s[0:1], 0x50
	s_waitcnt vmcnt(0)
	v_add_u32_e32 v10, 32, v180
	v_and_b32_e32 v5, 48, v180
	v_lshrrev_b32_e32 v6, 3, v202
	v_and_b32_e32 v11, 0x70, v10
	v_lshlrev_b32_e32 v12, 1, v10
	v_lshlrev_b32_e32 v3, 3, v202
	v_and_or_b32 v5, v6, 8, v5
	v_and_or_b32 v11, v12, 8, v11
	v_and_b32_e32 v4, 0x78, v3
	v_lshrrev_b32_e32 v5, 1, v5
	v_bfe_u32 v6, v3, 5, 2
	v_bfe_u32 v7, v202, 4, 2
	v_lshrrev_b32_e32 v11, 1, v11
	s_waitcnt lgkmcnt(0)
	s_add_u32 s11, s4, 0x8000000
	v_or_b32_e32 v5, v5, v6
	v_and_or_b32 v7, v203, 4, v7
	v_lshlrev_b32_e32 v8, 1, v4
	v_or_b32_e32 v6, v11, v6
	s_addc_u32 s22, s5, 0
	v_lshlrev_b32_e32 v5, 9, v5
	v_lshlrev_b32_e32 v7, 6, v7
	v_and_b32_e32 v9, 48, v8
	v_lshlrev_b32_e32 v6, 9, v6
	s_add_u32 s23, s4, 0xe000000
	v_or3_b32 v5, v5, v7, v9
	v_or3_b32 v7, v6, v7, v9
	v_lshlrev_b32_e32 v9, 4, v202
	v_lshlrev_b32_e32 v11, 1, v202
	s_addc_u32 s30, s5, 0
	s_lshr_b32 s31, s6, 8
	s_lshr_b32 s6, s6, 1
	v_bfe_u32 v0, v202, 5, 1
	v_and_b32_e32 v6, 0xc0, v9
	v_and_b32_e32 v11, 32, v11
	v_and_b32_e32 v3, 0x118, v3
	v_and_b32_e32 v188, 31, v202
	s_and_b32 s34, s6, 0x60
	v_or3_b32 v3, v11, v6, v3
	v_lshlrev_b32_e32 v11, 8, v180
	v_and_b32_e32 v12, 0x70, v202
	v_lshlrev_b32_e32 v10, 8, v10
	v_lshlrev_b32_e32 v191, 4, v0
	s_cmp_lg_u32 0, -1
	v_bitop3_b32 v11, v8, v11, v12 bitop3:0xde
	v_bitop3_b32 v13, v8, v10, v12 bitop3:0xde
	v_lshlrev_b32_e32 v8, 8, v188
	v_and_b32_e32 v9, 0x70, v9
	v_or_b32_e32 v10, 32, v191
	s_cselect_b32 s10, 0, 0
	v_bitop3_b32 v18, v10, v8, v9 bitop3:0xde
	v_or_b32_e32 v10, 64, v191
	v_add_u32_e32 v190, s10, v3
	v_bitop3_b32 v19, v10, v8, v9 bitop3:0xde
	v_or_b32_e32 v10, 0x60, v191
	v_lshlrev_b32_e32 v193, 2, v0
	s_addk_i32 s10, 0x4000
	v_lshlrev_b32_e32 v2, 3, v0
	v_bitop3_b32 v20, v10, v8, v9 bitop3:0xde
	v_or_b32_e32 v10, 0x80, v191
	v_add_u32_e32 v194, s10, v3
	v_mul_u32_u24_e32 v196, 0x440, v0
	v_or_b32_e32 v0, 1, v193
	s_movk_i32 s39, 0x110
	v_mov_b32_e32 v3, 0x990
	v_bitop3_b32 v21, v10, v8, v9 bitop3:0xde
	v_or_b32_e32 v10, 0xa0, v191
	v_mul_u32_u24_e32 v197, 0x110, v0
	v_mad_u32_u24 v198, v0, s39, v3
	v_sub_u32_e32 v0, v193, v188
	v_mul_u32_u24_e32 v6, 0xc00, v180
	v_bitop3_b32 v22, v10, v8, v9 bitop3:0xde
	v_or_b32_e32 v10, 0xc0, v191
	v_subrev_u32_e32 v199, s34, v0
	v_and_b32_e32 v0, 15, v202
	v_mov_b32_e32 v1, 0
	v_or_b32_e32 v4, v6, v4
	v_bitop3_b32 v23, v10, v8, v9 bitop3:0xde
	v_or_b32_e32 v10, 0xe0, v191
	v_lshlrev_b32_e32 v0, 4, v0
	v_and_b32_e32 v189, 63, v202
	v_add_u32_e32 v6, 0x18000, v4
	v_bitop3_b32 v15, v191, v8, v9 bitop3:0xde
	v_bitop3_b32 v9, v10, v8, v9 bitop3:0xde
	v_or_b32_e32 v192, s34, v188
	v_add_u32_e32 v8, 0x30000, v4
	v_add_u32_e32 v10, 0x48000, v4
	v_add_u32_e32 v12, 0x78000, v4
	v_add_u32_e32 v14, 0x60000, v4
	v_lshl_add_u64 v[16:17], s[4:5], 0, v[0:1]
	s_mov_b64 s[4:5], 0x81b1400
	s_movk_i32 s35, 0x1800
	v_mul_u32_u24_e32 v178, 0x1800, v188
	v_mov_b32_e32 v179, v1
	s_mov_b32 s36, 0x18000
	s_or_b32 s37, s6, 0xffffff9f
	v_cmp_gt_u32_e64 s[6:7], 32, v189
	s_movk_i32 s38, 0x4000
	v_sub_u32_e32 v195, v193, v192
	s_sub_i32 s40, 0, s34
	v_lshl_add_u64 v[182:183], v[16:17], 0, s[4:5]
	v_mov_b32_e32 v181, v1
	v_lshlrev_b32_e32 v184, 1, v2
	v_lshlrev_b32_e32 v200, 1, v4
	v_lshlrev_b32_e32 v201, 1, v6
	s_movk_i32 s41, 0x101
	s_mov_b32 s42, 0x10000
	s_mov_b32 s43, 0x413504f3
	s_mov_b32 s44, 0x42b504f3
	s_mov_b32 s10, 0x3e0293ee
	v_lshlrev_b32_e32 v204, 1, v8
	v_lshlrev_b32_e32 v205, 1, v10
	v_lshlrev_b32_e32 v206, 1, v12
	v_lshlrev_b32_e32 v207, 1, v14
	s_mov_b32 s45, 0xfff70000
	s_mov_b32 s46, 0xfffa0000
	s_mov_b64 s[12:13], 0xc0000
	s_mov_b32 s47, 0x8000
	s_mov_b32 s48, 0xc000
	s_mov_b32 s49, 0x14000
	s_mov_b32 s50, 0x1c000
	v_mov_b32_e32 v185, v1
	v_add_u32_e32 v208, 0, v5
	v_add_u32_e32 v209, 0, v7
	v_add_u32_e32 v210, 0, v11
	v_add_u32_e32 v211, 0, v13
	v_add_u32_e32 v212, 0, v15
	v_add_u32_e32 v213, 0, v18
	v_add_u32_e32 v214, 0, v19
	v_add_u32_e32 v215, 0, v20
	v_add_u32_e32 v216, 0, v21
	v_add_u32_e32 v217, 0, v22
	v_add_u32_e32 v218, 0, v23
	v_add_u32_e32 v219, 0, v9
	v_mov_b32_e32 v220, 0xf149f2ca
	s_mov_b32 s51, s2
	s_branch .LBB0_238
